# stack6: + nt (non-temporal) hint on read-once x loads (P0, P3 epilogue) and final output stores (P9)
# speedup vs baseline: 1.0292x; 1.0181x over previous
; DI uint4 cvt8(const float4 a, const float4 b) { uint4 r; r.x = pack2(a.x, a.y); r.y = pack2(a.z, a.w); r.z = pack2(b.x, b.y); r.w = pack2(b.z, b.w); return r; }
; DI void cvt_linear(const float* __restrict__ src, u16* __restrict__ dst, size_t n8, size_t gtid, size_t gsz) {
;   for (size_t i = gtid; i < n8; i += gsz) {
;     const float4 a = *(const float4*)(src + i * 8), b = *(const float4*)(src + i * 8 + 4);
;     *(uint4*)(dst + i * 8) = cvt8(a, b);
;   }
; }
.LBB0_9:
	global_load_dwordx4 v[12:15], v[6:7], off offset:-16 nt
	global_load_dwordx4 v[16:19], v[6:7], off nt
	v_lshl_add_u64 v[10:11], v[10:11], 0, s[8:9]
	v_cmp_lt_u64_e32 vcc, s[20:21], v[10:11]
	v_lshl_add_u64 v[6:7], v[6:7], 0, s[16:17]
	s_or_b64 s[18:19], vcc, s[18:19]
	s_waitcnt vmcnt(1)
	v_cvt_pk_bf16_f32 v12, v12, v13
	v_cvt_pk_bf16_f32 v13, v14, v15
	s_waitcnt vmcnt(0)
	v_cvt_pk_bf16_f32 v14, v16, v17
	v_cvt_pk_bf16_f32 v15, v18, v19
	global_store_dwordx4 v[8:9], v[12:15], off offset:-8
	v_lshl_add_u64 v[8:9], v[8:9], 0, s[14:15]
	s_andn2_b64 exec, exec, s[18:19]
	s_cbranch_execnz .LBB0_9

; DI unsigned pack2(float a, float b) { const f32x2 v = {a, b}; const bf16x2_t r = __builtin_convertvector(v, bf16x2_t); return __builtin_bit_cast(unsigned, r); }
; DI void outproj_epilogue(const Params& p, const char* smem, const int m0, const int n0) {
;   u16* rbuf = (u16*)(p.ws + WS_PU);
;   const float* ct = (const float*)smem;
; #pragma unroll 4
;   for (int i = 0; i < 16; ++i) {
;     const int c = threadIdx.x + NT * i, row = c >> 5, ch = c & 31;
;     const float4 y = *(const float4*)(ct + row * CT_PITCH + 4 * ch);
;     const size_t o = (size_t)(m0 + row) * 1024 + n0 + 4 * ch;
;     const float4 xv = *(const float4*)(p.x + o), bv = *(const float4*)(p.b_out + n0 + 4 * ch);
;     uint2 r; r.x = pack2(ALPHA * xv.x + y.x + bv.x, ALPHA * xv.y + y.y + bv.y); r.y = pack2(ALPHA * xv.z + y.z + bv.z, ALPHA * xv.w + y.w + bv.w);
;     *(uint2*)(rbuf + o) = r;
;   }
; }
.LBB0_294:
	s_ashr_i32 s27, s26, 31
	v_mov_b32_e32 v141, s27
	v_or_b32_e32 v140, s26, v130
	v_lshl_add_u64 v[138:139], s[26:27], 2, v[136:137]
	v_add_u32_e32 v162, s0, v149
	v_add_u32_e32 v163, s0, v151
	v_add_u32_e32 v164, s0, v153
	s_mov_b32 s0, 0
	v_mov_b32_e32 v165, v154
	v_mov_b32_e32 v166, v152
	v_mov_b32_e32 v167, v150
	v_lshrrev_b32_e32 v187, 4, v0
	v_sub_u32_e32 v184, v164, v153
	v_add_u32_e32 v187, v184, v187
	v_and_b32_e32 v184, 15, v0
	v_lshl_or_b32 v184, v184, 3, s26
	v_lshlrev_b32_e32 v164, 2, v184
	v_lshl_add_u32 v184, v187, 10, v184
	v_lshlrev_b32_e32 v185, 1, v184
	v_lshlrev_b32_e32 v184, 2, v184
	v_readlane_b32 s100, v239, 0
	v_readlane_b32 s101, v239, 1
	v_lshrrev_b32_e32 v187, 4, v0
	v_and_b32_e32 v186, 15, v0
	v_lshlrev_b32_e32 v186, 5, v186
	v_mul_u32_u24_e32 v187, 0x210, v187
	v_add_u32_e32 v186, v187, v186
	s_nop 1
	global_load_dwordx4 v[168:171], v164, s[100:101] offset:0
	global_load_dwordx4 v[172:175], v164, s[100:101] offset:16
	s_mov_b64 s[98:99], s[52:53]
	global_load_dwordx4 v[188:191], v184, s[98:99] offset:0 nt
	global_load_dwordx4 v[192:195], v184, s[98:99] offset:16 nt
	s_add_u32 s98, s98, 0x20000
	s_addc_u32 s99, s99, 0
	global_load_dwordx4 v[196:199], v184, s[98:99] offset:0 nt
	global_load_dwordx4 v[202:205], v184, s[98:99] offset:16 nt
	s_add_u32 s98, s98, 0x20000
	s_addc_u32 s99, s99, 0
	global_load_dwordx4 v[206:209], v184, s[98:99] offset:0 nt
	global_load_dwordx4 v[210:213], v184, s[98:99] offset:16 nt
	s_add_u32 s98, s98, 0x20000
	s_addc_u32 s99, s99, 0
	global_load_dwordx4 v[214:217], v184, s[98:99] offset:0 nt
	global_load_dwordx4 v[218:221], v184, s[98:99] offset:16 nt
	s_add_u32 s98, s98, 0x20000
	s_addc_u32 s99, s99, 0
	global_load_dwordx4 v[222:225], v184, s[98:99] offset:0 nt
	global_load_dwordx4 v[226:229], v184, s[98:99] offset:16 nt
	s_add_u32 s98, s98, 0x20000
	s_addc_u32 s99, s99, 0
	global_load_dwordx4 v[230:233], v184, s[98:99] offset:0 nt
	global_load_dwordx4 v[234:237], v184, s[98:99] offset:16 nt
	s_add_u32 s98, s98, 0x20000
	s_addc_u32 s99, s99, 0
	global_load_dwordx4 v[240:243], v184, s[98:99] offset:0 nt
	global_load_dwordx4 v[244:247], v184, s[98:99] offset:16 nt
	s_add_u32 s98, s98, 0x20000
	s_addc_u32 s99, s99, 0
	global_load_dwordx4 v[248:251], v184, s[98:99] offset:0 nt
	global_load_dwordx4 v[252:255], v184, s[98:99] offset:16 nt
	s_waitcnt lgkmcnt(0)
	s_barrier
	s_mov_b64 s[98:99], s[14:15]
	ds_read_b128 v[176:179], v186
	ds_read_b128 v[180:183], v186 offset:16
	s_waitcnt vmcnt(14) lgkmcnt(0)
	v_pk_fma_f32 v[188:189], v[188:189], s[24:25], v[176:177] op_sel_hi:[1,0,1]
	v_pk_fma_f32 v[190:191], v[190:191], s[24:25], v[178:179] op_sel_hi:[1,0,1]
	v_pk_fma_f32 v[192:193], v[192:193], s[24:25], v[180:181] op_sel_hi:[1,0,1]
	v_pk_fma_f32 v[194:195], v[194:195], s[24:25], v[182:183] op_sel_hi:[1,0,1]
	v_add_u32_e32 v186, 0x4200, v186
	ds_read_b128 v[176:179], v186
	ds_read_b128 v[180:183], v186 offset:16
	v_pk_add_f32 v[188:189], v[188:189], v[168:169]
	v_pk_add_f32 v[190:191], v[190:191], v[170:171]
	v_pk_add_f32 v[192:193], v[192:193], v[172:173]
	v_pk_add_f32 v[194:195], v[194:195], v[174:175]
	v_cvt_pk_bf16_f32 v188, v188, v189
	v_cvt_pk_bf16_f32 v189, v190, v191
	v_cvt_pk_bf16_f32 v190, v192, v193
	v_cvt_pk_bf16_f32 v191, v194, v195
	global_store_dwordx4 v185, v[188:191], s[98:99] offset:0
	s_add_u32 s98, s98, 0x10000
	s_addc_u32 s99, s99, 0
	s_waitcnt vmcnt(13) lgkmcnt(0)
	v_pk_fma_f32 v[196:197], v[196:197], s[24:25], v[176:177] op_sel_hi:[1,0,1]
	v_pk_fma_f32 v[198:199], v[198:199], s[24:25], v[178:179] op_sel_hi:[1,0,1]
	v_pk_fma_f32 v[202:203], v[202:203], s[24:25], v[180:181] op_sel_hi:[1,0,1]
	v_pk_fma_f32 v[204:205], v[204:205], s[24:25], v[182:183] op_sel_hi:[1,0,1]
	v_add_u32_e32 v186, 0x4200, v186
	ds_read_b128 v[176:179], v186
	ds_read_b128 v[180:183], v186 offset:16
	v_pk_add_f32 v[196:197], v[196:197], v[168:169]
	v_pk_add_f32 v[198:199], v[198:199], v[170:171]
	v_pk_add_f32 v[202:203], v[202:203], v[172:173]
	v_pk_add_f32 v[204:205], v[204:205], v[174:175]
	v_cvt_pk_bf16_f32 v196, v196, v197
	v_cvt_pk_bf16_f32 v197, v198, v199
	v_cvt_pk_bf16_f32 v198, v202, v203
	v_cvt_pk_bf16_f32 v199, v204, v205
	global_store_dwordx4 v185, v[196:199], s[98:99] offset:0
	s_add_u32 s98, s98, 0x10000
	s_addc_u32 s99, s99, 0
	s_waitcnt vmcnt(12) lgkmcnt(0)
	v_pk_fma_f32 v[206:207], v[206:207], s[24:25], v[176:177] op_sel_hi:[1,0,1]
	v_pk_fma_f32 v[208:209], v[208:209], s[24:25], v[178:179] op_sel_hi:[1,0,1]
	v_pk_fma_f32 v[210:211], v[210:211], s[24:25], v[180:181] op_sel_hi:[1,0,1]
	v_pk_fma_f32 v[212:213], v[212:213], s[24:25], v[182:183] op_sel_hi:[1,0,1]
	v_add_u32_e32 v186, 0x4200, v186
	ds_read_b128 v[176:179], v186
	ds_read_b128 v[180:183], v186 offset:16
	v_pk_add_f32 v[206:207], v[206:207], v[168:169]
	v_pk_add_f32 v[208:209], v[208:209], v[170:171]
	v_pk_add_f32 v[210:211], v[210:211], v[172:173]
	v_pk_add_f32 v[212:213], v[212:213], v[174:175]
	v_cvt_pk_bf16_f32 v206, v206, v207
	v_cvt_pk_bf16_f32 v207, v208, v209
	v_cvt_pk_bf16_f32 v208, v210, v211
	v_cvt_pk_bf16_f32 v209, v212, v213
	global_store_dwordx4 v185, v[206:209], s[98:99] offset:0
	s_add_u32 s98, s98, 0x10000
	s_addc_u32 s99, s99, 0
	s_waitcnt vmcnt(11) lgkmcnt(0)
; DI unsigned pack2(float a, float b) { const f32x2 v = {a, b}; const bf16x2_t r = __builtin_convertvector(v, bf16x2_t); return __builtin_bit_cast(unsigned, r); }
; DI void outproj_epilogue(const Params& p, const char* smem, const int m0, const int n0) {
;   u16* rbuf = (u16*)(p.ws + WS_PU);
;   const float* ct = (const float*)smem;
; #pragma unroll 4
;   for (int i = 0; i < 16; ++i) {
;     const int c = threadIdx.x + NT * i, row = c >> 5, ch = c & 31;
;     const float4 y = *(const float4*)(ct + row * CT_PITCH + 4 * ch);
;     const size_t o = (size_t)(m0 + row) * 1024 + n0 + 4 * ch;
;     const float4 xv = *(const float4*)(p.x + o), bv = *(const float4*)(p.b_out + n0 + 4 * ch);
;     uint2 r; r.x = pack2(ALPHA * xv.x + y.x + bv.x, ALPHA * xv.y + y.y + bv.y); r.y = pack2(ALPHA * xv.z + y.z + bv.z, ALPHA * xv.w + y.w + bv.w);
;     *(uint2*)(rbuf + o) = r;
;   }
; }
	v_pk_fma_f32 v[214:215], v[214:215], s[24:25], v[176:177] op_sel_hi:[1,0,1]
	v_pk_fma_f32 v[216:217], v[216:217], s[24:25], v[178:179] op_sel_hi:[1,0,1]
	v_pk_fma_f32 v[218:219], v[218:219], s[24:25], v[180:181] op_sel_hi:[1,0,1]
	v_pk_fma_f32 v[220:221], v[220:221], s[24:25], v[182:183] op_sel_hi:[1,0,1]
	v_add_u32_e32 v186, 0x4200, v186
	ds_read_b128 v[176:179], v186
	ds_read_b128 v[180:183], v186 offset:16
	v_pk_add_f32 v[214:215], v[214:215], v[168:169]
	v_pk_add_f32 v[216:217], v[216:217], v[170:171]
	v_pk_add_f32 v[218:219], v[218:219], v[172:173]
	v_pk_add_f32 v[220:221], v[220:221], v[174:175]
	v_cvt_pk_bf16_f32 v214, v214, v215
	v_cvt_pk_bf16_f32 v215, v216, v217
	v_cvt_pk_bf16_f32 v216, v218, v219
	v_cvt_pk_bf16_f32 v217, v220, v221
	global_store_dwordx4 v185, v[214:217], s[98:99] offset:0
	s_add_u32 s98, s98, 0x10000
	s_addc_u32 s99, s99, 0
	s_waitcnt vmcnt(10) lgkmcnt(0)
	v_pk_fma_f32 v[222:223], v[222:223], s[24:25], v[176:177] op_sel_hi:[1,0,1]
	v_pk_fma_f32 v[224:225], v[224:225], s[24:25], v[178:179] op_sel_hi:[1,0,1]
	v_pk_fma_f32 v[226:227], v[226:227], s[24:25], v[180:181] op_sel_hi:[1,0,1]
	v_pk_fma_f32 v[228:229], v[228:229], s[24:25], v[182:183] op_sel_hi:[1,0,1]
	v_add_u32_e32 v186, 0x4200, v186
	ds_read_b128 v[176:179], v186
	ds_read_b128 v[180:183], v186 offset:16
	v_pk_add_f32 v[222:223], v[222:223], v[168:169]
	v_pk_add_f32 v[224:225], v[224:225], v[170:171]
	v_pk_add_f32 v[226:227], v[226:227], v[172:173]
	v_pk_add_f32 v[228:229], v[228:229], v[174:175]
	v_cvt_pk_bf16_f32 v222, v222, v223
	v_cvt_pk_bf16_f32 v223, v224, v225
	v_cvt_pk_bf16_f32 v224, v226, v227
	v_cvt_pk_bf16_f32 v225, v228, v229
	global_store_dwordx4 v185, v[222:225], s[98:99] offset:0
	s_add_u32 s98, s98, 0x10000
	s_addc_u32 s99, s99, 0
	s_waitcnt vmcnt(9) lgkmcnt(0)
	v_pk_fma_f32 v[230:231], v[230:231], s[24:25], v[176:177] op_sel_hi:[1,0,1]
	v_pk_fma_f32 v[232:233], v[232:233], s[24:25], v[178:179] op_sel_hi:[1,0,1]
	v_pk_fma_f32 v[234:235], v[234:235], s[24:25], v[180:181] op_sel_hi:[1,0,1]
	v_pk_fma_f32 v[236:237], v[236:237], s[24:25], v[182:183] op_sel_hi:[1,0,1]
	v_add_u32_e32 v186, 0x4200, v186
	ds_read_b128 v[176:179], v186
	ds_read_b128 v[180:183], v186 offset:16
	v_pk_add_f32 v[230:231], v[230:231], v[168:169]
	v_pk_add_f32 v[232:233], v[232:233], v[170:171]
	v_pk_add_f32 v[234:235], v[234:235], v[172:173]
	v_pk_add_f32 v[236:237], v[236:237], v[174:175]
	v_cvt_pk_bf16_f32 v230, v230, v231
	v_cvt_pk_bf16_f32 v231, v232, v233
	v_cvt_pk_bf16_f32 v232, v234, v235
	v_cvt_pk_bf16_f32 v233, v236, v237
	global_store_dwordx4 v185, v[230:233], s[98:99] offset:0
	s_add_u32 s98, s98, 0x10000
	s_addc_u32 s99, s99, 0
	s_waitcnt vmcnt(8) lgkmcnt(0)
	v_pk_fma_f32 v[240:241], v[240:241], s[24:25], v[176:177] op_sel_hi:[1,0,1]
	v_pk_fma_f32 v[242:243], v[242:243], s[24:25], v[178:179] op_sel_hi:[1,0,1]
	v_pk_fma_f32 v[244:245], v[244:245], s[24:25], v[180:181] op_sel_hi:[1,0,1]
	v_pk_fma_f32 v[246:247], v[246:247], s[24:25], v[182:183] op_sel_hi:[1,0,1]
	v_add_u32_e32 v186, 0x4200, v186
	ds_read_b128 v[176:179], v186
	ds_read_b128 v[180:183], v186 offset:16
	v_pk_add_f32 v[240:241], v[240:241], v[168:169]
	v_pk_add_f32 v[242:243], v[242:243], v[170:171]
	v_pk_add_f32 v[244:245], v[244:245], v[172:173]
	v_pk_add_f32 v[246:247], v[246:247], v[174:175]
	v_cvt_pk_bf16_f32 v240, v240, v241
	v_cvt_pk_bf16_f32 v241, v242, v243
	v_cvt_pk_bf16_f32 v242, v244, v245
	v_cvt_pk_bf16_f32 v243, v246, v247
	global_store_dwordx4 v185, v[240:243], s[98:99] offset:0
	s_add_u32 s98, s98, 0x10000
	s_addc_u32 s99, s99, 0
	s_waitcnt vmcnt(7) lgkmcnt(0)
	v_pk_fma_f32 v[248:249], v[248:249], s[24:25], v[176:177] op_sel_hi:[1,0,1]
	v_pk_fma_f32 v[250:251], v[250:251], s[24:25], v[178:179] op_sel_hi:[1,0,1]
	v_pk_fma_f32 v[252:253], v[252:253], s[24:25], v[180:181] op_sel_hi:[1,0,1]
	v_pk_fma_f32 v[254:255], v[254:255], s[24:25], v[182:183] op_sel_hi:[1,0,1]
	v_pk_add_f32 v[248:249], v[248:249], v[168:169]
	v_pk_add_f32 v[250:251], v[250:251], v[170:171]
	v_pk_add_f32 v[252:253], v[252:253], v[172:173]
	v_pk_add_f32 v[254:255], v[254:255], v[174:175]
	v_cvt_pk_bf16_f32 v248, v248, v249
	v_cvt_pk_bf16_f32 v249, v250, v251
	v_cvt_pk_bf16_f32 v250, v252, v253
	v_cvt_pk_bf16_f32 v251, v254, v255
	global_store_dwordx4 v185, v[248:251], s[98:99] offset:0
	v_readfirstlane_b32 s0, v0
	s_and_b32 s1, s0, 0xffffff00
	s_cmpk_lg_i32 s1, 0x100
	s_barrier
	s_cbranch_scc1 .LBB0_298
; DI unsigned pack2(float a, float b) { const f32x2 v = {a, b}; const bf16x2_t r = __builtin_convertvector(v, bf16x2_t); return __builtin_bit_cast(unsigned, r); }
; template <int HF>
; DI void stage_acc_big(const f32x4 (&acc)[8][4], char* smem, const int g, const int r16) {
;   const int w = __builtin_amdgcn_readfirstlane(threadIdx.x >> 6), wm = w & 1, wn = w >> 1;
;   if ((wn >> 1) != HF) return;
;   float* ct = (float*)smem;
; #pragma unroll
;   for (int mi = 0; mi < 8; ++mi)
; #pragma unroll
;     for (int ni = 0; ni < 4; ++ni)
; #pragma unroll
;       for (int j = 0; j < 4; ++j) ct[(128 * wm + 16 * mi + 4 * g + j) * CT_PITCH + 64 * (wn & 1) + 16 * ni + r16] = acc[mi][ni][j];
; }
; DI void outproj_epilogue(const Params& p, const char* smem, const int m0, const int n0) {
;   u16* rbuf = (u16*)(p.ws + WS_PU);
;   const float* ct = (const float*)smem;
; #pragma unroll 4
;   for (int i = 0; i < 16; ++i) {
;     const int c = threadIdx.x + NT * i, row = c >> 5, ch = c & 31;
;     const float4 y = *(const float4*)(ct + row * CT_PITCH + 4 * ch);
;     const size_t o = (size_t)(m0 + row) * 1024 + n0 + 4 * ch;
;     const float4 xv = *(const float4*)(p.x + o), bv = *(const float4*)(p.b_out + n0 + 4 * ch);
;     uint2 r; r.x = pack2(ALPHA * xv.x + y.x + bv.x, ALPHA * xv.y + y.y + bv.y); r.y = pack2(ALPHA * xv.z + y.z + bv.z, ALPHA * xv.w + y.w + bv.w);
;     *(uint2*)(rbuf + o) = r;
;   }
; }
	s_lshl_b32 s0, s0, 1
	s_and_b32 s1, s0, 0x80
	v_or_b32_e32 v140, s1, v148
	s_and_b32 s0, s0, 0x100
	v_mul_u32_u24_e32 v140, 0x210, v140
	v_add3_u32 v140, v143, s0, v140
	ds_write2_b32 v140, v126, v122 offset1:16
	ds_write2_b32 v140, v127, v123 offset0:132 offset1:148
	v_add_u32_e32 v122, 0x400, v140
	ds_write2_b32 v122, v128, v124 offset0:8 offset1:24
	ds_write2_b32 v122, v129, v125 offset0:140 offset1:156
	ds_write2_b32 v140, v118, v114 offset0:32 offset1:48
	ds_write2_b32 v140, v119, v115 offset0:164 offset1:180
	ds_write2_b32 v122, v120, v116 offset0:40 offset1:56
	ds_write2_b32 v122, v121, v117 offset0:172 offset1:188
	v_add_u32_e32 v114, 0x2000, v140
	ds_write2_b32 v114, v110, v106 offset0:64 offset1:80
	ds_write2_b32 v114, v111, v107 offset0:196 offset1:212
	v_add_u32_e32 v106, 0x2400, v140
	ds_write2_b32 v106, v112, v108 offset0:72 offset1:88
	ds_write2_b32 v106, v113, v109 offset0:204 offset1:220
	ds_write2_b32 v114, v102, v98 offset0:96 offset1:112
	ds_write2_b32 v114, v103, v99 offset0:228 offset1:244
	ds_write2_b32 v106, v104, v100 offset0:104 offset1:120
	ds_write2_b32 v106, v105, v101 offset0:236 offset1:252
	v_add_u32_e32 v98, 0x4000, v140
	ds_write2_b32 v98, v94, v90 offset0:128 offset1:144
	v_add_u32_e32 v90, 0x4400, v140
	ds_write2_b32 v90, v95, v91 offset0:4 offset1:20
	ds_write2_b32 v90, v96, v92 offset0:136 offset1:152
	v_add_u32_e32 v91, 0x4800, v140
	ds_write2_b32 v91, v97, v93 offset0:12 offset1:28
	ds_write2_b32 v98, v86, v82 offset0:160 offset1:176
	ds_write2_b32 v90, v87, v83 offset0:36 offset1:52
	ds_write2_b32 v90, v88, v84 offset0:168 offset1:184
	ds_write2_b32 v91, v89, v85 offset0:44 offset1:60
	v_add_u32_e32 v82, 0x6000, v140
	ds_write2_b32 v82, v78, v74 offset0:192 offset1:208
	v_add_u32_e32 v74, 0x6400, v140
	ds_write2_b32 v74, v79, v75 offset0:68 offset1:84
	ds_write2_b32 v74, v80, v76 offset0:200 offset1:216
	v_add_u32_e32 v75, 0x6800, v140
	ds_write2_b32 v75, v81, v77 offset0:76 offset1:92
	ds_write2_b32 v82, v66, v62 offset0:224 offset1:240
	ds_write2_b32 v74, v67, v63 offset0:100 offset1:116
	ds_write2_b32 v74, v68, v64 offset0:232 offset1:248
	ds_write2_b32 v75, v69, v65 offset0:108 offset1:124
	v_add_u32_e32 v62, 0x8400, v140
	ds_write2_b32 v62, v58, v54 offset1:16
	ds_write2_b32 v62, v59, v55 offset0:132 offset1:148
	v_add_u32_e32 v54, 0x8800, v140
	ds_write2_b32 v54, v60, v56 offset0:8 offset1:24
	ds_write2_b32 v54, v61, v57 offset0:140 offset1:156
	ds_write2_b32 v62, v50, v46 offset0:32 offset1:48
	ds_write2_b32 v62, v51, v47 offset0:164 offset1:180
	ds_write2_b32 v54, v52, v48 offset0:40 offset1:56
	ds_write2_b32 v54, v53, v49 offset0:172 offset1:188
	v_add_u32_e32 v46, 0xa400, v140
	ds_write2_b32 v46, v42, v38 offset0:64 offset1:80
	ds_write2_b32 v46, v43, v39 offset0:196 offset1:212
	v_add_u32_e32 v38, 0xa800, v140
	ds_write2_b32 v38, v44, v40 offset0:72 offset1:88
	ds_write2_b32 v38, v45, v41 offset0:204 offset1:220
	ds_write2_b32 v46, v34, v30 offset0:96 offset1:112
	ds_write2_b32 v46, v35, v31 offset0:228 offset1:244
	ds_write2_b32 v38, v36, v32 offset0:104 offset1:120
	ds_write2_b32 v38, v37, v33 offset0:236 offset1:252
	v_add_u32_e32 v30, 0xc400, v140
	ds_write2_b32 v30, v26, v22 offset0:128 offset1:144
	v_add_u32_e32 v22, 0xc800, v140
	ds_write2_b32 v22, v27, v23 offset0:4 offset1:20
	ds_write2_b32 v22, v28, v24 offset0:136 offset1:152
	v_add_u32_e32 v23, 0xcc00, v140
	ds_write2_b32 v23, v29, v25 offset0:12 offset1:28
	ds_write2_b32 v30, v18, v14 offset0:160 offset1:176
	ds_write2_b32 v22, v19, v15 offset0:36 offset1:52
	ds_write2_b32 v22, v20, v16 offset0:168 offset1:184
	ds_write2_b32 v23, v21, v17 offset0:44 offset1:60
	v_add_u32_e32 v14, 0xe400, v140
	ds_write2_b32 v14, v10, v6 offset0:192 offset1:208
	v_add_u32_e32 v6, 0xe800, v140
	ds_write2_b32 v6, v11, v7 offset0:68 offset1:84
	ds_write2_b32 v6, v12, v8 offset0:200 offset1:216
	v_add_u32_e32 v7, 0xec00, v140
	ds_write2_b32 v7, v13, v9 offset0:76 offset1:92
	ds_write2_b32 v14, v2, v70 offset0:224 offset1:240
	ds_write2_b32 v6, v3, v71 offset0:100 offset1:116
	ds_write2_b32 v6, v4, v72 offset0:232 offset1:248
	ds_write2_b32 v7, v5, v73 offset0:108 offset1:124
.LBB0_298:
	s_or_b32 s0, s26, 0x80
	s_ashr_i32 s1, s0, 31
	v_mov_b32_e32 v3, s1
	v_or_b32_e32 v2, s0, v130
	v_lshl_add_u64 v[4:5], s[26:27], 0, v[130:131]
	s_mov_b32 s0, 0
	v_mov_b32_e32 v6, v154
	v_mov_b32_e32 v7, v152
	v_mov_b32_e32 v8, v150
	v_lshrrev_b32_e32 v187, 4, v0
	v_and_b32_e32 v186, 15, v0
	v_lshlrev_b32_e32 v186, 5, v186
	v_mul_u32_u24_e32 v187, 0x210, v187
	v_add_u32_e32 v186, v187, v186
	s_nop 1
	global_load_dwordx4 v[168:171], v164, s[100:101] offset:512
	global_load_dwordx4 v[172:175], v164, s[100:101] offset:528
	s_mov_b64 s[98:99], s[52:53]
	global_load_dwordx4 v[188:191], v184, s[98:99] offset:512 nt
	global_load_dwordx4 v[192:195], v184, s[98:99] offset:528 nt
	s_add_u32 s98, s98, 0x20000
	s_addc_u32 s99, s99, 0
	global_load_dwordx4 v[196:199], v184, s[98:99] offset:512 nt
	global_load_dwordx4 v[202:205], v184, s[98:99] offset:528 nt
	s_add_u32 s98, s98, 0x20000
	s_addc_u32 s99, s99, 0
	global_load_dwordx4 v[206:209], v184, s[98:99] offset:512 nt
	global_load_dwordx4 v[210:213], v184, s[98:99] offset:528 nt
	s_add_u32 s98, s98, 0x20000
	s_addc_u32 s99, s99, 0
	global_load_dwordx4 v[214:217], v184, s[98:99] offset:512 nt
	global_load_dwordx4 v[218:221], v184, s[98:99] offset:528 nt
	s_add_u32 s98, s98, 0x20000
	s_addc_u32 s99, s99, 0
	global_load_dwordx4 v[222:225], v184, s[98:99] offset:512 nt
	global_load_dwordx4 v[226:229], v184, s[98:99] offset:528 nt
	s_add_u32 s98, s98, 0x20000
	s_addc_u32 s99, s99, 0
	global_load_dwordx4 v[230:233], v184, s[98:99] offset:512 nt
	global_load_dwordx4 v[234:237], v184, s[98:99] offset:528 nt
	s_add_u32 s98, s98, 0x20000
	s_addc_u32 s99, s99, 0
	global_load_dwordx4 v[240:243], v184, s[98:99] offset:512 nt
	global_load_dwordx4 v[244:247], v184, s[98:99] offset:528 nt
	s_add_u32 s98, s98, 0x20000
	s_addc_u32 s99, s99, 0
	global_load_dwordx4 v[248:251], v184, s[98:99] offset:512 nt
	global_load_dwordx4 v[252:255], v184, s[98:99] offset:528 nt
	s_waitcnt lgkmcnt(0)
	s_barrier
; DI unsigned pack2(float a, float b) { const f32x2 v = {a, b}; const bf16x2_t r = __builtin_convertvector(v, bf16x2_t); return __builtin_bit_cast(unsigned, r); }
; DI void outproj_epilogue(const Params& p, const char* smem, const int m0, const int n0) {
;     ...
;   for (int i = 0; i < 16; ++i) {
;     const int c = threadIdx.x + NT * i, row = c >> 5, ch = c & 31;
;     const float4 y = *(const float4*)(ct + row * CT_PITCH + 4 * ch);
;     const size_t o = (size_t)(m0 + row) * 1024 + n0 + 4 * ch;
;     const float4 xv = *(const float4*)(p.x + o), bv = *(const float4*)(p.b_out + n0 + 4 * ch);
;     uint2 r; r.x = pack2(ALPHA * xv.x + y.x + bv.x, ALPHA * xv.y + y.y + bv.y); r.y = pack2(ALPHA * xv.z + y.z + bv.z, ALPHA * xv.w + y.w + bv.w);
;     *(uint2*)(rbuf + o) = r;
;   }
	s_mov_b64 s[98:99], s[14:15]
	ds_read_b128 v[176:179], v186
	ds_read_b128 v[180:183], v186 offset:16
	s_waitcnt vmcnt(14) lgkmcnt(0)
	v_pk_fma_f32 v[188:189], v[188:189], s[24:25], v[176:177] op_sel_hi:[1,0,1]
	v_pk_fma_f32 v[190:191], v[190:191], s[24:25], v[178:179] op_sel_hi:[1,0,1]
	v_pk_fma_f32 v[192:193], v[192:193], s[24:25], v[180:181] op_sel_hi:[1,0,1]
	v_pk_fma_f32 v[194:195], v[194:195], s[24:25], v[182:183] op_sel_hi:[1,0,1]
	v_add_u32_e32 v186, 0x4200, v186
	ds_read_b128 v[176:179], v186
	ds_read_b128 v[180:183], v186 offset:16
	v_pk_add_f32 v[188:189], v[188:189], v[168:169]
	v_pk_add_f32 v[190:191], v[190:191], v[170:171]
	v_pk_add_f32 v[192:193], v[192:193], v[172:173]
	v_pk_add_f32 v[194:195], v[194:195], v[174:175]
	v_cvt_pk_bf16_f32 v188, v188, v189
	v_cvt_pk_bf16_f32 v189, v190, v191
	v_cvt_pk_bf16_f32 v190, v192, v193
	v_cvt_pk_bf16_f32 v191, v194, v195
	global_store_dwordx4 v185, v[188:191], s[98:99] offset:256
	s_add_u32 s98, s98, 0x10000
	s_addc_u32 s99, s99, 0
	s_waitcnt vmcnt(13) lgkmcnt(0)
	v_pk_fma_f32 v[196:197], v[196:197], s[24:25], v[176:177] op_sel_hi:[1,0,1]
	v_pk_fma_f32 v[198:199], v[198:199], s[24:25], v[178:179] op_sel_hi:[1,0,1]
	v_pk_fma_f32 v[202:203], v[202:203], s[24:25], v[180:181] op_sel_hi:[1,0,1]
	v_pk_fma_f32 v[204:205], v[204:205], s[24:25], v[182:183] op_sel_hi:[1,0,1]
	v_add_u32_e32 v186, 0x4200, v186
	ds_read_b128 v[176:179], v186
	ds_read_b128 v[180:183], v186 offset:16
	v_pk_add_f32 v[196:197], v[196:197], v[168:169]
	v_pk_add_f32 v[198:199], v[198:199], v[170:171]
	v_pk_add_f32 v[202:203], v[202:203], v[172:173]
	v_pk_add_f32 v[204:205], v[204:205], v[174:175]
	v_cvt_pk_bf16_f32 v196, v196, v197
	v_cvt_pk_bf16_f32 v197, v198, v199
	v_cvt_pk_bf16_f32 v198, v202, v203
	v_cvt_pk_bf16_f32 v199, v204, v205
	global_store_dwordx4 v185, v[196:199], s[98:99] offset:256
	s_add_u32 s98, s98, 0x10000
	s_addc_u32 s99, s99, 0
	s_waitcnt vmcnt(12) lgkmcnt(0)
	v_pk_fma_f32 v[206:207], v[206:207], s[24:25], v[176:177] op_sel_hi:[1,0,1]
	v_pk_fma_f32 v[208:209], v[208:209], s[24:25], v[178:179] op_sel_hi:[1,0,1]
	v_pk_fma_f32 v[210:211], v[210:211], s[24:25], v[180:181] op_sel_hi:[1,0,1]
	v_pk_fma_f32 v[212:213], v[212:213], s[24:25], v[182:183] op_sel_hi:[1,0,1]
	v_add_u32_e32 v186, 0x4200, v186
	ds_read_b128 v[176:179], v186
	ds_read_b128 v[180:183], v186 offset:16
	v_pk_add_f32 v[206:207], v[206:207], v[168:169]
	v_pk_add_f32 v[208:209], v[208:209], v[170:171]
	v_pk_add_f32 v[210:211], v[210:211], v[172:173]
	v_pk_add_f32 v[212:213], v[212:213], v[174:175]
	v_cvt_pk_bf16_f32 v206, v206, v207
	v_cvt_pk_bf16_f32 v207, v208, v209
	v_cvt_pk_bf16_f32 v208, v210, v211
	v_cvt_pk_bf16_f32 v209, v212, v213
	global_store_dwordx4 v185, v[206:209], s[98:99] offset:256
	s_add_u32 s98, s98, 0x10000
	s_addc_u32 s99, s99, 0
	s_waitcnt vmcnt(11) lgkmcnt(0)
	v_pk_fma_f32 v[214:215], v[214:215], s[24:25], v[176:177] op_sel_hi:[1,0,1]
	v_pk_fma_f32 v[216:217], v[216:217], s[24:25], v[178:179] op_sel_hi:[1,0,1]
	v_pk_fma_f32 v[218:219], v[218:219], s[24:25], v[180:181] op_sel_hi:[1,0,1]
	v_pk_fma_f32 v[220:221], v[220:221], s[24:25], v[182:183] op_sel_hi:[1,0,1]
	v_add_u32_e32 v186, 0x4200, v186
	ds_read_b128 v[176:179], v186
	ds_read_b128 v[180:183], v186 offset:16
	v_pk_add_f32 v[214:215], v[214:215], v[168:169]
	v_pk_add_f32 v[216:217], v[216:217], v[170:171]
	v_pk_add_f32 v[218:219], v[218:219], v[172:173]
	v_pk_add_f32 v[220:221], v[220:221], v[174:175]
	v_cvt_pk_bf16_f32 v214, v214, v215
	v_cvt_pk_bf16_f32 v215, v216, v217
	v_cvt_pk_bf16_f32 v216, v218, v219
	v_cvt_pk_bf16_f32 v217, v220, v221
	global_store_dwordx4 v185, v[214:217], s[98:99] offset:256
	s_add_u32 s98, s98, 0x10000
	s_addc_u32 s99, s99, 0
	s_waitcnt vmcnt(10) lgkmcnt(0)
; DI unsigned pack2(float a, float b) { const f32x2 v = {a, b}; const bf16x2_t r = __builtin_convertvector(v, bf16x2_t); return __builtin_bit_cast(unsigned, r); }
; DI void outproj_epilogue(const Params& p, const char* smem, const int m0, const int n0) {
;     ...
;   for (int i = 0; i < 16; ++i) {
;     const int c = threadIdx.x + NT * i, row = c >> 5, ch = c & 31;
;     const float4 y = *(const float4*)(ct + row * CT_PITCH + 4 * ch);
;     const size_t o = (size_t)(m0 + row) * 1024 + n0 + 4 * ch;
;     const float4 xv = *(const float4*)(p.x + o), bv = *(const float4*)(p.b_out + n0 + 4 * ch);
;     uint2 r; r.x = pack2(ALPHA * xv.x + y.x + bv.x, ALPHA * xv.y + y.y + bv.y); r.y = pack2(ALPHA * xv.z + y.z + bv.z, ALPHA * xv.w + y.w + bv.w);
;     *(uint2*)(rbuf + o) = r;
;   }
; DI void phase_outproj(const Params& p, char* smem) {
;     ...
;   for (int tile = blockIdx.x, kit = 0; tile < (T / 256) * NTN; tile += gridDim.x, ++kit) {
;     int mt_, nt_; tile_coords<4>(tile, kit, T / 256, NTN, mt_, nt_);
;     const int m0 = mt_ * 256, n0b = nt_ * 256;
;     f32x4 acc[8][4];
;     gemm_tile_big(mix, wt, DM, m0, n0b, smem, acc);
;     stage_acc_big<0>(acc, smem, g, r16);
;     __syncthreads();
;     outproj_epilogue(p, smem, m0, n0b);
;     __syncthreads();
;     stage_acc_big<1>(acc, smem, g, r16);
;     __syncthreads();
;     outproj_epilogue(p, smem, m0, n0b + 128);
;     __syncthreads();
	v_pk_fma_f32 v[222:223], v[222:223], s[24:25], v[176:177] op_sel_hi:[1,0,1]
	v_pk_fma_f32 v[224:225], v[224:225], s[24:25], v[178:179] op_sel_hi:[1,0,1]
	v_pk_fma_f32 v[226:227], v[226:227], s[24:25], v[180:181] op_sel_hi:[1,0,1]
	v_pk_fma_f32 v[228:229], v[228:229], s[24:25], v[182:183] op_sel_hi:[1,0,1]
	v_add_u32_e32 v186, 0x4200, v186
	ds_read_b128 v[176:179], v186
	ds_read_b128 v[180:183], v186 offset:16
	v_pk_add_f32 v[222:223], v[222:223], v[168:169]
	v_pk_add_f32 v[224:225], v[224:225], v[170:171]
	v_pk_add_f32 v[226:227], v[226:227], v[172:173]
	v_pk_add_f32 v[228:229], v[228:229], v[174:175]
	v_cvt_pk_bf16_f32 v222, v222, v223
	v_cvt_pk_bf16_f32 v223, v224, v225
	v_cvt_pk_bf16_f32 v224, v226, v227
	v_cvt_pk_bf16_f32 v225, v228, v229
	global_store_dwordx4 v185, v[222:225], s[98:99] offset:256
	s_add_u32 s98, s98, 0x10000
	s_addc_u32 s99, s99, 0
	s_waitcnt vmcnt(9) lgkmcnt(0)
	v_pk_fma_f32 v[230:231], v[230:231], s[24:25], v[176:177] op_sel_hi:[1,0,1]
	v_pk_fma_f32 v[232:233], v[232:233], s[24:25], v[178:179] op_sel_hi:[1,0,1]
	v_pk_fma_f32 v[234:235], v[234:235], s[24:25], v[180:181] op_sel_hi:[1,0,1]
	v_pk_fma_f32 v[236:237], v[236:237], s[24:25], v[182:183] op_sel_hi:[1,0,1]
	v_add_u32_e32 v186, 0x4200, v186
	ds_read_b128 v[176:179], v186
	ds_read_b128 v[180:183], v186 offset:16
	v_pk_add_f32 v[230:231], v[230:231], v[168:169]
	v_pk_add_f32 v[232:233], v[232:233], v[170:171]
	v_pk_add_f32 v[234:235], v[234:235], v[172:173]
	v_pk_add_f32 v[236:237], v[236:237], v[174:175]
	v_cvt_pk_bf16_f32 v230, v230, v231
	v_cvt_pk_bf16_f32 v231, v232, v233
	v_cvt_pk_bf16_f32 v232, v234, v235
	v_cvt_pk_bf16_f32 v233, v236, v237
	global_store_dwordx4 v185, v[230:233], s[98:99] offset:256
	s_add_u32 s98, s98, 0x10000
	s_addc_u32 s99, s99, 0
	s_waitcnt vmcnt(8) lgkmcnt(0)
	v_pk_fma_f32 v[240:241], v[240:241], s[24:25], v[176:177] op_sel_hi:[1,0,1]
	v_pk_fma_f32 v[242:243], v[242:243], s[24:25], v[178:179] op_sel_hi:[1,0,1]
	v_pk_fma_f32 v[244:245], v[244:245], s[24:25], v[180:181] op_sel_hi:[1,0,1]
	v_pk_fma_f32 v[246:247], v[246:247], s[24:25], v[182:183] op_sel_hi:[1,0,1]
	v_add_u32_e32 v186, 0x4200, v186
	ds_read_b128 v[176:179], v186
	ds_read_b128 v[180:183], v186 offset:16
	v_pk_add_f32 v[240:241], v[240:241], v[168:169]
	v_pk_add_f32 v[242:243], v[242:243], v[170:171]
	v_pk_add_f32 v[244:245], v[244:245], v[172:173]
	v_pk_add_f32 v[246:247], v[246:247], v[174:175]
	v_cvt_pk_bf16_f32 v240, v240, v241
	v_cvt_pk_bf16_f32 v241, v242, v243
	v_cvt_pk_bf16_f32 v242, v244, v245
	v_cvt_pk_bf16_f32 v243, v246, v247
	global_store_dwordx4 v185, v[240:243], s[98:99] offset:256
	s_add_u32 s98, s98, 0x10000
	s_addc_u32 s99, s99, 0
	s_waitcnt vmcnt(7) lgkmcnt(0)
	v_pk_fma_f32 v[248:249], v[248:249], s[24:25], v[176:177] op_sel_hi:[1,0,1]
	v_pk_fma_f32 v[250:251], v[250:251], s[24:25], v[178:179] op_sel_hi:[1,0,1]
	v_pk_fma_f32 v[252:253], v[252:253], s[24:25], v[180:181] op_sel_hi:[1,0,1]
	v_pk_fma_f32 v[254:255], v[254:255], s[24:25], v[182:183] op_sel_hi:[1,0,1]
	v_pk_add_f32 v[248:249], v[248:249], v[168:169]
	v_pk_add_f32 v[250:251], v[250:251], v[170:171]
	v_pk_add_f32 v[252:253], v[252:253], v[172:173]
	v_pk_add_f32 v[254:255], v[254:255], v[174:175]
	v_cvt_pk_bf16_f32 v248, v248, v249
	v_cvt_pk_bf16_f32 v249, v250, v251
	v_cvt_pk_bf16_f32 v250, v252, v253
	v_cvt_pk_bf16_f32 v251, v254, v255
	global_store_dwordx4 v185, v[248:251], s[98:99] offset:256
	s_add_i32 s31, s31, s3
	s_add_i32 s34, s34, 1
	s_cmpk_lt_i32 s31, 0x200
	s_barrier
	s_cbranch_scc1 .LBB0_286
	s_branch .LBB0_303

; DI float bflo(unsigned w) { return __uint_as_float(w << 16); }
; DI float bfhi(unsigned w) { return __uint_as_float(w & 0xffff0000u); }
; DI void phase_ln2(const Params& p) {
;     ...
;   for (int tb = blockIdx.x; tb < T / 8; tb += 2 * gridDim.x) {
;     const int tb1 = tb + (int)gridDim.x < T / 8 ? tb + (int)gridDim.x : tb;
;     const int tt[2] = {tb * 8 + w, tb1 * 8 + w};
;     float4 v[2][4];
; #pragma unroll
;     for (int z = 0; z < 2; ++z)
; #pragma unroll
;       for (int k = 0; k < 4; ++k) {
;         const uint2 hq = *(const uint2*)(h1b + (size_t)tt[z] * 1024 + 256 * k + 4 * lane);
;         const uint2 yq = *(const uint2*)(ybuf + (size_t)tt[z] * 1024 + 256 * k + 4 * lane);
;         const float4 y = float4{bflo(yq.x), bfhi(yq.x), bflo(yq.y), bfhi(yq.y)};
;         v[z][k] = float4{ALPHA * bflo(hq.x) + y.x, ALPHA * bfhi(hq.x) + y.y, ALPHA * bflo(hq.y) + y.z, ALPHA * bfhi(hq.y) + y.w};
;       }
; #pragma unroll
;     for (int z = 0; z < 2; ++z) {
;       float sm = 0.f;
; #pragma unroll
;       for (int k = 0; k < 4; ++k) sm += v[z][k].x + v[z][k].y + v[z][k].z + v[z][k].w;
.LBB0_614:
	s_add_i32 s0, s7, s2
	s_cmpk_lt_i32 s0, 0x1000
	s_cselect_b32 s0, s0, s2
	s_ashr_i32 s5, s4, 31
	s_lshl_b32 s14, s0, 3
	s_lshl_b64 s[0:1], s[4:5], 11
	s_add_i32 s14, s14, s3
	v_lshl_add_u64 v[50:51], v[34:35], 0, s[0:1]
	v_lshl_add_u64 v[42:43], v[32:33], 0, s[0:1]
	global_load_dwordx2 v[52:53], v[50:51], off
	global_load_dwordx2 v[54:55], v[42:43], off
	global_load_dwordx2 v[56:57], v[50:51], off offset:512
	global_load_dwordx2 v[58:59], v[42:43], off offset:512
	global_load_dwordx2 v[60:61], v[50:51], off offset:1024
	global_load_dwordx2 v[62:63], v[42:43], off offset:1024
	global_load_dwordx2 v[64:65], v[50:51], off offset:1536
	global_load_dwordx2 v[66:67], v[42:43], off offset:1536
	s_ashr_i32 s15, s14, 31
	s_lshl_b64 s[0:1], s[14:15], 11
	v_lshl_add_u64 v[68:69], v[34:35], 0, s[0:1]
	v_lshl_add_u64 v[50:51], v[32:33], 0, s[0:1]
	global_load_dwordx2 v[70:71], v[68:69], off
	global_load_dwordx2 v[72:73], v[50:51], off
	global_load_dwordx2 v[74:75], v[68:69], off offset:512
	global_load_dwordx2 v[76:77], v[50:51], off offset:512
	global_load_dwordx2 v[78:79], v[68:69], off offset:1024
	global_load_dwordx2 v[80:81], v[50:51], off offset:1024
	global_load_dwordx2 v[82:83], v[50:51], off offset:1536
	global_load_dwordx2 v[84:85], v[68:69], off offset:1536
	s_lshl_b64 s[12:13], s[4:5], 12
	s_add_i32 s2, s2, s9
	s_add_i32 s4, s4, s10
	v_lshl_add_u64 v[40:41], v[36:37], 0, s[12:13]
	s_lshl_b64 s[12:13], s[14:15], 12
	s_cmpk_lt_i32 s2, 0x1000
	v_lshl_add_u64 v[42:43], v[36:37], 0, s[12:13]
	s_waitcnt vmcnt(15)
	v_lshlrev_b32_e32 v50, 16, v52
	v_and_b32_e32 v51, 0xffff0000, v52
	v_lshlrev_b32_e32 v52, 16, v53
	v_and_b32_e32 v53, 0xffff0000, v53
	s_waitcnt vmcnt(14)
	v_lshlrev_b32_e32 v68, 16, v54
	v_and_b32_e32 v69, 0xffff0000, v54
	v_lshlrev_b32_e32 v54, 16, v55
	v_and_b32_e32 v55, 0xffff0000, v55
	s_waitcnt vmcnt(13)
	v_lshlrev_b32_e32 v86, 16, v56
	v_and_b32_e32 v87, 0xffff0000, v56
	s_waitcnt vmcnt(12)
	v_lshlrev_b32_e32 v88, 16, v58
	v_and_b32_e32 v89, 0xffff0000, v58
	v_lshlrev_b32_e32 v56, 16, v57
	v_and_b32_e32 v57, 0xffff0000, v57
	v_lshlrev_b32_e32 v58, 16, v59
	v_and_b32_e32 v59, 0xffff0000, v59
	s_waitcnt vmcnt(9)
	v_lshlrev_b32_e32 v94, 16, v64
	v_and_b32_e32 v95, 0xffff0000, v64
	v_lshlrev_b32_e32 v64, 16, v65
	v_and_b32_e32 v65, 0xffff0000, v65
	s_waitcnt vmcnt(8)
	v_lshlrev_b32_e32 v96, 16, v66
	v_and_b32_e32 v97, 0xffff0000, v66
	v_lshlrev_b32_e32 v66, 16, v67
	v_and_b32_e32 v67, 0xffff0000, v67
	v_pk_fma_f32 v[50:51], v[68:69], s[6:7], v[50:51] op_sel_hi:[1,0,1]
	v_pk_fma_f32 v[52:53], v[54:55], s[6:7], v[52:53] op_sel_hi:[1,0,1]
	v_pk_fma_f32 v[54:55], v[88:89], s[6:7], v[86:87] op_sel_hi:[1,0,1]
	v_lshlrev_b32_e32 v90, 16, v60
	v_and_b32_e32 v91, 0xffff0000, v60
	v_lshlrev_b32_e32 v60, 16, v61
	v_and_b32_e32 v61, 0xffff0000, v61
	v_lshlrev_b32_e32 v92, 16, v62
	v_and_b32_e32 v93, 0xffff0000, v62
	v_lshlrev_b32_e32 v62, 16, v63
	v_and_b32_e32 v63, 0xffff0000, v63
	v_pk_fma_f32 v[56:57], v[58:59], s[6:7], v[56:57] op_sel_hi:[1,0,1]
	v_pk_fma_f32 v[64:65], v[66:67], s[6:7], v[64:65] op_sel_hi:[1,0,1]
	v_mov_b32_e32 v66, v50
	v_mov_b32_e32 v67, v54
	v_mov_b32_e32 v68, v51
	v_mov_b32_e32 v69, v55
	v_pk_fma_f32 v[58:59], v[92:93], s[6:7], v[90:91] op_sel_hi:[1,0,1]
	v_pk_fma_f32 v[60:61], v[62:63], s[6:7], v[60:61] op_sel_hi:[1,0,1]
	v_pk_fma_f32 v[62:63], v[96:97], s[6:7], v[94:95] op_sel_hi:[1,0,1]
	v_mov_b32_e32 v86, v52
	v_mov_b32_e32 v87, v56
	s_waitcnt vmcnt(7)
	v_lshlrev_b32_e32 v98, 16, v70
	v_and_b32_e32 v99, 0xffff0000, v70
	v_lshlrev_b32_e32 v70, 16, v71
	v_and_b32_e32 v71, 0xffff0000, v71
	s_waitcnt vmcnt(6)
	v_lshlrev_b32_e32 v100, 16, v72
	v_and_b32_e32 v101, 0xffff0000, v72
	v_lshlrev_b32_e32 v72, 16, v73
	v_and_b32_e32 v73, 0xffff0000, v73
	s_waitcnt vmcnt(5)
	v_lshlrev_b32_e32 v102, 16, v74
	v_and_b32_e32 v103, 0xffff0000, v74
	s_waitcnt vmcnt(4)
	v_lshlrev_b32_e32 v104, 16, v76
	v_and_b32_e32 v105, 0xffff0000, v76
	v_pk_add_f32 v[66:67], v[66:67], v[68:69]
	v_mov_b32_e32 v88, v53
	v_mov_b32_e32 v89, v57
	v_mov_b32_e32 v90, v58
	v_mov_b32_e32 v91, v62
	v_mov_b32_e32 v92, v59
	v_mov_b32_e32 v93, v63
	v_lshlrev_b32_e32 v74, 16, v75
	v_and_b32_e32 v75, 0xffff0000, v75
	v_lshlrev_b32_e32 v76, 16, v77
	v_and_b32_e32 v77, 0xffff0000, v77
	s_waitcnt vmcnt(0)
	v_lshlrev_b32_e32 v110, 16, v84
	v_and_b32_e32 v111, 0xffff0000, v84
	v_lshlrev_b32_e32 v84, 16, v85
	v_and_b32_e32 v85, 0xffff0000, v85
	v_lshlrev_b32_e32 v112, 16, v82
	v_and_b32_e32 v113, 0xffff0000, v82
	v_lshlrev_b32_e32 v82, 16, v83
	v_and_b32_e32 v83, 0xffff0000, v83
	v_pk_add_f32 v[66:67], v[66:67], v[86:87]
	v_pk_fma_f32 v[86:87], v[100:101], s[6:7], v[98:99] op_sel_hi:[1,0,1]
	v_pk_fma_f32 v[70:71], v[72:73], s[6:7], v[70:71] op_sel_hi:[1,0,1]
	v_pk_fma_f32 v[72:73], v[104:105], s[6:7], v[102:103] op_sel_hi:[1,0,1]
	v_mov_b32_e32 v94, v60
	v_mov_b32_e32 v95, v64
	v_lshlrev_b32_e32 v106, 16, v78
	v_and_b32_e32 v107, 0xffff0000, v78
	v_lshlrev_b32_e32 v78, 16, v79
	v_and_b32_e32 v79, 0xffff0000, v79
	v_lshlrev_b32_e32 v108, 16, v80
	v_and_b32_e32 v109, 0xffff0000, v80
	v_lshlrev_b32_e32 v80, 16, v81
	v_and_b32_e32 v81, 0xffff0000, v81
	v_pk_add_f32 v[68:69], v[90:91], v[92:93]
	v_pk_fma_f32 v[74:75], v[76:77], s[6:7], v[74:75] op_sel_hi:[1,0,1]
	v_pk_fma_f32 v[82:83], v[82:83], s[6:7], v[84:85] op_sel_hi:[1,0,1]
	v_pk_add_f32 v[66:67], v[88:89], v[66:67]
	v_mov_b32_e32 v84, v86
	v_mov_b32_e32 v85, v72
	v_mov_b32_e32 v88, v87
	v_mov_b32_e32 v89, v73
	v_mov_b32_e32 v96, v61
	v_mov_b32_e32 v97, v65
	v_pk_add_f32 v[68:69], v[68:69], v[94:95]
	v_pk_fma_f32 v[76:77], v[108:109], s[6:7], v[106:107] op_sel_hi:[1,0,1]
	v_pk_fma_f32 v[78:79], v[80:81], s[6:7], v[78:79] op_sel_hi:[1,0,1]
	v_pk_fma_f32 v[80:81], v[112:113], s[6:7], v[110:111] op_sel_hi:[1,0,1]
	v_mov_b32_e32 v90, v70
	v_mov_b32_e32 v91, v74
	v_add_f32_e32 v49, 0, v66
	v_pk_add_f32 v[84:85], v[84:85], v[88:89]
	v_pk_add_f32 v[68:69], v[96:97], v[68:69]
	v_mov_b32_e32 v92, v71
	v_mov_b32_e32 v93, v75
	v_mov_b32_e32 v94, v76
	v_mov_b32_e32 v95, v80
	v_mov_b32_e32 v96, v77
	v_mov_b32_e32 v97, v81
	v_add_f32_e32 v49, v49, v67
	v_pk_add_f32 v[66:67], v[84:85], v[90:91]
	v_mov_b32_e32 v98, v78
	v_mov_b32_e32 v99, v82
	v_pk_add_f32 v[88:89], v[94:95], v[96:97]
	v_pk_add_f32 v[66:67], v[92:93], v[66:67]
	v_mov_b32_e32 v100, v79
	v_mov_b32_e32 v101, v83
	v_pk_add_f32 v[84:85], v[88:89], v[98:99]
	v_add_f32_e32 v49, v49, v68
	v_add_f32_e32 v66, 0, v66
	v_pk_add_f32 v[84:85], v[100:101], v[84:85]
	v_add_f32_e32 v49, v49, v69
	v_add_f32_e32 v66, v66, v67
	ds_bpermute_b32 v68, v39, v49
	v_add_f32_e32 v66, v66, v84
	v_add_f32_e32 v66, v66, v85
	ds_bpermute_b32 v67, v39, v66
	s_waitcnt lgkmcnt(1)
; DI void phase_ln2(const Params& p) {
;     ...
;       const float mean = wave_sum(sm) * (1.f / 1024.f);
;       float sq = 0.f;
; #pragma unroll
;       for (int k = 0; k < 4; ++k) { float d; d = v[z][k].x - mean; sq += d * d; d = v[z][k].y - mean; sq += d * d; d = v[z][k].z - mean; sq += d * d; d = v[z][k].w - mean; sq += d * d; }
;       const float rstd = rsqrtf(wave_sum(sq) * (1.f / 1024.f) + LN_EPS);
	v_add_f32_e32 v49, v49, v68
	ds_bpermute_b32 v68, v44, v49
	s_waitcnt lgkmcnt(1)
	v_add_f32_e32 v66, v66, v67
	ds_bpermute_b32 v67, v44, v66
	s_waitcnt lgkmcnt(1)
	v_add_f32_e32 v49, v49, v68
	ds_bpermute_b32 v68, v45, v49
	s_waitcnt lgkmcnt(1)
	v_add_f32_e32 v66, v66, v67
	ds_bpermute_b32 v67, v45, v66
	s_waitcnt lgkmcnt(1)
	v_add_f32_e32 v49, v49, v68
	ds_bpermute_b32 v68, v46, v49
	s_waitcnt lgkmcnt(1)
	v_add_f32_e32 v66, v66, v67
	ds_bpermute_b32 v67, v46, v66
	s_waitcnt lgkmcnt(1)
	v_add_f32_e32 v49, v49, v68
	ds_bpermute_b32 v68, v47, v49
	s_waitcnt lgkmcnt(1)
	v_add_f32_e32 v66, v66, v67
	ds_bpermute_b32 v67, v47, v66
	s_waitcnt lgkmcnt(1)
	v_add_f32_e32 v49, v49, v68
	ds_bpermute_b32 v68, v48, v49
	s_waitcnt lgkmcnt(1)
	v_add_f32_e32 v84, v66, v67
	ds_bpermute_b32 v85, v48, v84
	s_waitcnt lgkmcnt(1)
	v_add_f32_e32 v49, v49, v68
	v_mul_f32_e32 v66, 0x3a800000, v49
	v_pk_add_f32 v[50:51], v[50:51], v[66:67] op_sel_hi:[1,0] neg_lo:[0,1] neg_hi:[0,1]
	s_waitcnt lgkmcnt(0)
	v_add_f32_e32 v49, v84, v85
	v_mov_b32_e32 v85, v50
	v_mul_f32_e32 v84, 0x3a800000, v49
	v_pk_add_f32 v[86:87], v[86:87], v[84:85] op_sel_hi:[1,0] neg_lo:[0,1] neg_hi:[0,1]
	v_mov_b32_e32 v89, v51
	v_mov_b32_e32 v88, v87
	v_pk_add_f32 v[52:53], v[52:53], v[66:67] op_sel_hi:[1,0] neg_lo:[0,1] neg_hi:[0,1]
	v_pk_add_f32 v[70:71], v[70:71], v[84:85] op_sel_hi:[1,0] neg_lo:[0,1] neg_hi:[0,1]
	v_pk_add_f32 v[72:73], v[72:73], v[84:85] op_sel_hi:[1,0] neg_lo:[0,1] neg_hi:[0,1]
	v_pk_add_f32 v[74:75], v[74:75], v[84:85] op_sel_hi:[1,0] neg_lo:[0,1] neg_hi:[0,1]
	v_pk_add_f32 v[76:77], v[76:77], v[84:85] op_sel_hi:[1,0] neg_lo:[0,1] neg_hi:[0,1]
	v_pk_add_f32 v[78:79], v[78:79], v[84:85] op_sel_hi:[1,0] neg_lo:[0,1] neg_hi:[0,1]
	v_pk_add_f32 v[80:81], v[80:81], v[84:85] op_sel_hi:[1,0] neg_lo:[0,1] neg_hi:[0,1]
	v_pk_add_f32 v[82:83], v[82:83], v[84:85] op_sel_hi:[1,0] neg_lo:[0,1] neg_hi:[0,1]
	v_mov_b32_e32 v84, v86
	v_pk_mul_f32 v[88:89], v[88:89], v[88:89]
	v_mov_b32_e32 v91, v52
	v_mov_b32_e32 v90, v70
	v_pk_fma_f32 v[84:85], v[84:85], v[84:85], v[88:89]
	v_pk_add_f32 v[54:55], v[54:55], v[66:67] op_sel_hi:[1,0] neg_lo:[0,1] neg_hi:[0,1]
	v_mov_b32_e32 v93, v53
	v_mov_b32_e32 v92, v71
	v_pk_fma_f32 v[84:85], v[90:91], v[90:91], v[84:85]
	v_mov_b32_e32 v95, v54
	v_mov_b32_e32 v94, v72
	v_pk_fma_f32 v[84:85], v[92:93], v[92:93], v[84:85]
	v_pk_add_f32 v[56:57], v[56:57], v[66:67] op_sel_hi:[1,0] neg_lo:[0,1] neg_hi:[0,1]
	v_mov_b32_e32 v97, v55
	v_mov_b32_e32 v96, v73
	v_pk_fma_f32 v[84:85], v[94:95], v[94:95], v[84:85]
	v_mov_b32_e32 v99, v56
	v_mov_b32_e32 v98, v74
	v_pk_fma_f32 v[84:85], v[96:97], v[96:97], v[84:85]
	v_pk_add_f32 v[58:59], v[58:59], v[66:67] op_sel_hi:[1,0] neg_lo:[0,1] neg_hi:[0,1]
	v_mov_b32_e32 v101, v57
	v_mov_b32_e32 v100, v75
	v_pk_fma_f32 v[84:85], v[98:99], v[98:99], v[84:85]
	v_mov_b32_e32 v103, v58
	v_mov_b32_e32 v102, v76
	v_pk_fma_f32 v[84:85], v[100:101], v[100:101], v[84:85]
	v_pk_add_f32 v[60:61], v[60:61], v[66:67] op_sel_hi:[1,0] neg_lo:[0,1] neg_hi:[0,1]
	v_mov_b32_e32 v105, v59
	v_mov_b32_e32 v104, v77
	v_pk_fma_f32 v[84:85], v[102:103], v[102:103], v[84:85]
	v_pk_add_f32 v[62:63], v[62:63], v[66:67] op_sel_hi:[1,0] neg_lo:[0,1] neg_hi:[0,1]
	v_mov_b32_e32 v107, v60
	v_mov_b32_e32 v106, v78
	v_pk_fma_f32 v[84:85], v[104:105], v[104:105], v[84:85]
	v_pk_add_f32 v[64:65], v[64:65], v[66:67] op_sel_hi:[1,0] neg_lo:[0,1] neg_hi:[0,1]
	v_pk_mul_f32 v[66:67], v[62:63], v[62:63]
	v_mov_b32_e32 v109, v61
	v_pk_mul_f32 v[114:115], v[80:81], v[80:81]
	v_mov_b32_e32 v108, v79
	v_pk_fma_f32 v[84:85], v[106:107], v[106:107], v[84:85]
	v_mov_b32_e32 v111, v66
	v_mov_b32_e32 v110, v114
	v_pk_fma_f32 v[84:85], v[108:109], v[108:109], v[84:85]
	v_pk_mul_f32 v[68:69], v[64:65], v[64:65]
	v_pk_mul_f32 v[116:117], v[82:83], v[82:83]
	v_mov_b32_e32 v66, v115
	v_pk_add_f32 v[84:85], v[110:111], v[84:85]
	v_mov_b32_e32 v113, v68
	v_mov_b32_e32 v112, v116
	v_pk_add_f32 v[66:67], v[66:67], v[84:85]
	v_mov_b32_e32 v68, v117
	v_pk_add_f32 v[66:67], v[112:113], v[66:67]
	s_nop 0
	v_pk_add_f32 v[66:67], v[68:69], v[66:67]
	ds_bpermute_b32 v69, v39, v67
	ds_bpermute_b32 v68, v39, v66
	s_waitcnt lgkmcnt(0)
; DI void phase_ln2(const Params& p) {
;     ...
;       for (int k = 0; k < 4; ++k) { float d; d = v[z][k].x - mean; sq += d * d; d = v[z][k].y - mean; sq += d * d; d = v[z][k].z - mean; sq += d * d; d = v[z][k].w - mean; sq += d * d; }
;       const float rstd = rsqrtf(wave_sum(sq) * (1.f / 1024.f) + LN_EPS);
; #pragma unroll
;       for (int k = 0; k < 4; ++k) {
;         float4 o;
;         o.x = (v[z][k].x - mean) * rstd * gg[k].x + bb[k].x; o.y = (v[z][k].y - mean) * rstd * gg[k].y + bb[k].y;
;         o.z = (v[z][k].z - mean) * rstd * gg[k].z + bb[k].z; o.w = (v[z][k].w - mean) * rstd * gg[k].w + bb[k].w;
;         *(float4*)(p.out + (size_t)tt[z] * 1024 + 256 * k + 4 * lane) = o;
;       }
	v_pk_add_f32 v[66:67], v[66:67], v[68:69]
	ds_bpermute_b32 v69, v44, v67
	ds_bpermute_b32 v68, v44, v66
	s_waitcnt lgkmcnt(0)
	v_pk_add_f32 v[66:67], v[66:67], v[68:69]
	ds_bpermute_b32 v69, v45, v67
	ds_bpermute_b32 v68, v45, v66
	s_waitcnt lgkmcnt(0)
	v_pk_add_f32 v[66:67], v[66:67], v[68:69]
	ds_bpermute_b32 v69, v46, v67
	ds_bpermute_b32 v68, v46, v66
	s_waitcnt lgkmcnt(0)
	v_pk_add_f32 v[66:67], v[66:67], v[68:69]
	ds_bpermute_b32 v69, v47, v67
	ds_bpermute_b32 v68, v47, v66
	s_waitcnt lgkmcnt(0)
	v_pk_add_f32 v[66:67], v[66:67], v[68:69]
	ds_bpermute_b32 v69, v48, v67
	ds_bpermute_b32 v68, v48, v66
	s_waitcnt lgkmcnt(0)
	v_pk_add_f32 v[66:67], v[66:67], v[68:69]
	s_nop 0
	v_pk_fma_f32 v[66:67], v[66:67], s[8:9], v[38:39] op_sel_hi:[1,0,0]
	s_nop 0
	v_mul_f32_e32 v49, 0x4b800000, v67
	v_cmp_gt_f32_e64 s[0:1], s11, v67
	v_mul_f32_e32 v68, 0x4b800000, v66
	v_cmp_gt_f32_e32 vcc, s11, v66
	v_cndmask_b32_e64 v49, v67, v49, s[0:1]
	v_rsq_f32_e32 v49, v49
	v_cndmask_b32_e32 v66, v66, v68, vcc
	v_rsq_f32_e32 v67, v66
	v_mul_f32_e32 v66, 0x45800000, v49
	v_cndmask_b32_e64 v66, v49, v66, s[0:1]
	v_mul_f32_e32 v68, 0x45800000, v67
	v_cndmask_b32_e32 v68, v67, v68, vcc
	v_pk_mul_f32 v[50:51], v[50:51], v[66:67] op_sel_hi:[1,0]
	v_pk_mul_f32 v[52:53], v[52:53], v[66:67] op_sel_hi:[1,0]
	v_pk_mul_f32 v[54:55], v[54:55], v[66:67] op_sel_hi:[1,0]
	v_pk_mul_f32 v[56:57], v[56:57], v[66:67] op_sel_hi:[1,0]
	v_pk_mul_f32 v[58:59], v[58:59], v[66:67] op_sel_hi:[1,0]
	v_pk_mul_f32 v[60:61], v[60:61], v[66:67] op_sel_hi:[1,0]
	v_pk_mul_f32 v[62:63], v[62:63], v[66:67] op_sel_hi:[1,0]
	v_pk_mul_f32 v[64:65], v[64:65], v[66:67] op_sel_hi:[1,0]
	v_pk_mul_f32 v[66:67], v[86:87], v[68:69] op_sel_hi:[1,0]
	v_pk_mul_f32 v[70:71], v[70:71], v[68:69] op_sel_hi:[1,0]
	v_pk_mul_f32 v[72:73], v[72:73], v[68:69] op_sel_hi:[1,0]
	v_pk_mul_f32 v[74:75], v[74:75], v[68:69] op_sel_hi:[1,0]
	v_pk_mul_f32 v[76:77], v[76:77], v[68:69] op_sel_hi:[1,0]
	v_pk_mul_f32 v[78:79], v[78:79], v[68:69] op_sel_hi:[1,0]
	v_pk_mul_f32 v[80:81], v[80:81], v[68:69] op_sel_hi:[1,0]
	v_pk_mul_f32 v[82:83], v[82:83], v[68:69] op_sel_hi:[1,0]
	v_pk_fma_f32 v[50:51], v[0:1], v[50:51], v[8:9]
	v_pk_fma_f32 v[52:53], v[2:3], v[52:53], v[10:11]
	v_pk_fma_f32 v[54:55], v[4:5], v[54:55], v[12:13]
	v_pk_fma_f32 v[56:57], v[6:7], v[56:57], v[14:15]
	v_pk_fma_f32 v[58:59], v[16:17], v[58:59], v[24:25]
	v_pk_fma_f32 v[60:61], v[18:19], v[60:61], v[26:27]
	v_pk_fma_f32 v[62:63], v[20:21], v[62:63], v[28:29]
	v_pk_fma_f32 v[64:65], v[22:23], v[64:65], v[30:31]
	v_pk_fma_f32 v[66:67], v[0:1], v[66:67], v[8:9]
	v_pk_fma_f32 v[68:69], v[2:3], v[70:71], v[10:11]
	v_pk_fma_f32 v[70:71], v[4:5], v[72:73], v[12:13]
	v_pk_fma_f32 v[72:73], v[6:7], v[74:75], v[14:15]
	v_pk_fma_f32 v[74:75], v[16:17], v[76:77], v[24:25]
	v_pk_fma_f32 v[76:77], v[18:19], v[78:79], v[26:27]
	v_pk_fma_f32 v[78:79], v[20:21], v[80:81], v[28:29]
	v_pk_fma_f32 v[80:81], v[22:23], v[82:83], v[30:31]
	global_store_dwordx4 v[40:41], v[50:53], off nt
	global_store_dwordx4 v[40:41], v[54:57], off offset:1024 nt
	global_store_dwordx4 v[40:41], v[58:61], off offset:2048 nt
	global_store_dwordx4 v[40:41], v[62:65], off offset:3072 nt
	global_store_dwordx4 v[42:43], v[66:69], off nt
	global_store_dwordx4 v[42:43], v[70:73], off offset:1024 nt
	global_store_dwordx4 v[42:43], v[74:77], off offset:2048 nt
	global_store_dwordx4 v[42:43], v[78:81], off offset:3072 nt
	s_cbranch_scc1 .LBB0_614
